# ping-pong attention loop: up-front QK fragment reads issued first in the matrix segment, before the V-tile write and the prefetch loads
# baseline (speedup 1.0000x reference)
; __device__ __forceinline__ void finishSM(f32x16& p0, f32x16& p1, float alpha, float& l_reg, bf16x8& pa0, bf16x8& pa1, bf16x8& pa2, bf16x8& pa3) {
; #pragma unroll
;     for (int r = 0; r < 16; ++r) p1[r] = __builtin_amdgcn_exp2f(p1[r]);
;     float ps = 0;
; #pragma unroll
;     for (int r = 0; r < 16; ++r) ps += p0[r];
; #pragma unroll
;     for (int r = 0; r < 16; ++r) ps += p1[r];
;     { auto rr = __builtin_amdgcn_permlane32_swap(__float_as_uint(ps), __float_as_uint(ps), false, false);
;       ps = __uint_as_float(rr[0]) + __uint_as_float(rr[1]); }
;     l_reg = l_reg * alpha + ps;
;     ...
;     PK4(p0, 0, pa0); PK4(p0, 8, pa1); PK4(p1, 0, pa2); PK4(p1, 8, pa3);
.Lp5_lead:
.LBB0_1299:
	v_exp_f32_e32 v209, v150
	v_add_f32_e32 v150, v220, v219
	v_add_f32_e32 v150, v221, v150
	v_add_f32_e32 v150, v222, v150
	v_add_f32_e32 v150, v223, v150
	v_add_f32_e32 v150, v225, v150
	v_add_f32_e32 v150, v224, v150
	v_add_f32_e32 v150, v226, v150
	v_add_f32_e32 v150, v211, v150
	v_add_f32_e32 v150, v212, v150
	v_exp_f32_e32 v194, v194
	v_exp_f32_e32 v195, v195
	v_exp_f32_e32 v192, v192
	v_exp_f32_e32 v193, v193
	v_exp_f32_e32 v158, v158
	v_exp_f32_e32 v159, v159
	v_exp_f32_e32 v207, v154
	v_exp_f32_e32 v208, v155
	v_exp_f32_e32 v210, v151
	v_exp_f32_e32 v160, v160
	v_exp_f32_e32 v161, v161
	v_exp_f32_e32 v227, v156
	v_cvt_pk_bf16_f32 v151, v224, v226
	v_cvt_pk_bf16_f32 v154, v214, v216
	v_cvt_pk_bf16_f32 v155, v217, v218
	v_cvt_pk_bf16_f32 v156, v194, v195
	v_exp_f32_e32 v228, v157
	v_exp_f32_e32 v229, v152
	v_exp_f32_e32 v230, v153
	v_cvt_pk_bf16_f32 v152, v211, v212
	v_cvt_pk_bf16_f32 v153, v213, v215
	v_cvt_pk_bf16_f32 v157, v192, v193
	v_cvt_pk_bf16_f32 v211, v229, v230
	v_add_f32_e32 v249, v213, v150
	v_add_f32_e32 v249, v215, v249
	v_add_f32_e32 v249, v214, v249
	v_add_f32_e32 v249, v216, v249
	v_add_f32_e32 v249, v217, v249
	v_add_f32_e32 v249, v218, v249
	v_add_f32_e32 v249, v194, v249
	v_add_f32_e32 v248, v195, v249
	v_add_f32_e32 v248, v192, v248
	v_add_f32_e32 v248, v193, v248
	v_add_f32_e32 v248, v158, v248
	v_add_f32_e32 v248, v159, v248
	v_add_f32_e32 v248, v207, v248
	v_add_f32_e32 v248, v208, v248
	v_add_f32_e32 v248, v209, v248
	v_add_f32_e32 v248, v210, v248
	v_add_f32_e32 v248, v160, v248
	v_add_f32_e32 v248, v161, v248
	v_add_f32_e32 v248, v227, v248
	v_add_f32_e32 v248, v228, v248
	v_add_f32_e32 v248, v229, v248
	v_add_f32_e32 v181, v230, v248
	v_cvt_pk_bf16_f32 v148, v219, v220
	v_cvt_pk_bf16_f32 v149, v221, v222
	v_cvt_pk_bf16_f32 v150, v223, v225
	v_cvt_pk_bf16_f32 v158, v158, v159
	v_cvt_pk_bf16_f32 v159, v207, v208
	v_cvt_pk_bf16_f32 v208, v209, v210
	v_cvt_pk_bf16_f32 v210, v227, v228
	v_cvt_pk_bf16_f32 v209, v160, v161
	s_waitcnt lgkmcnt(0)
	s_barrier
	ds_read_b128 v[66:69], v199 offset:49152
	ds_read_b128 v[82:85], v199 offset:57344
	ds_read_b128 v[172:175], v200 offset:49152
	ds_read_b128 v[232:235], v200 offset:57344
	ds_read_b128 v[236:239], v201 offset:49152
	ds_read_b128 v[240:243], v201 offset:57344
	ds_read_b128 v[244:247], v202 offset:49152
	s_cmp_eq_u32 s76, 0
	s_cbranch_scc1 .Lp5_vw_a
	s_waitcnt vmcnt(0)
	ds_write_b128 v197, v[130:133] offset:16384
	ds_write_b128 v198, v[134:137] offset:16384
.Lp5_vw_a:
	global_load_dwordx2 v[146:147], v179, s[68:69] offset:-8
	s_add_u32 s98, s16, 0x40000
	s_addc_u32 s99, s17, 0
	global_load_dwordx4 v[130:133], v188, s[98:99]
	s_add_u32 s98, s16, 0x50000
	s_addc_u32 s99, s17, 0
	global_load_dwordx4 v[134:137], v188, s[98:99]
	s_add_u32 s98, s100, 0x40000
	s_addc_u32 s99, s101, 0
	global_load_dwordx4 v[138:141], v188, s[98:99]
	s_add_u32 s98, s100, 0x50000
	s_addc_u32 s99, s101, 0
	global_load_dwordx4 v[142:145], v188, s[98:99]
	s_waitcnt lgkmcnt(6)
	v_mfma_f32_32x32x16_bf16 v[66:81], v[66:69], v[126:129], 0
	s_waitcnt lgkmcnt(5)
	v_mfma_f32_32x32x16_bf16 v[82:97], v[82:85], v[126:129], 0
	s_waitcnt lgkmcnt(4)
	v_mfma_f32_32x32x16_bf16 v[66:81], v[172:175], v[122:125], v[66:81]
	ds_read_b128 v[172:175], v202 offset:57344
	s_waitcnt lgkmcnt(4)
	v_mfma_f32_32x32x16_bf16 v[82:97], v[232:235], v[122:125], v[82:97]
	ds_read_b128 v[232:235], v199 offset:49280
	s_waitcnt lgkmcnt(4)
	v_mfma_f32_32x32x16_bf16 v[66:81], v[236:239], v[118:121], v[66:81]
	ds_read_b128 v[236:239], v199 offset:57472
	s_waitcnt lgkmcnt(4)
	v_mfma_f32_32x32x16_bf16 v[82:97], v[240:243], v[118:121], v[82:97]
	ds_read_b128 v[240:243], v200 offset:49280
	s_waitcnt lgkmcnt(4)
	v_mfma_f32_32x32x16_bf16 v[66:81], v[244:247], v[114:117], v[66:81]
	ds_read_b128 v[244:247], v200 offset:57472
	s_waitcnt lgkmcnt(4)
	v_mfma_f32_32x32x16_bf16 v[82:97], v[172:175], v[114:117], v[82:97]
	ds_read_b128 v[172:175], v201 offset:49280
	s_waitcnt lgkmcnt(4)
	v_mfma_f32_32x32x16_bf16 v[66:81], v[232:235], v[110:113], v[66:81]
	ds_read_b128 v[232:235], v201 offset:57472
	s_waitcnt lgkmcnt(4)
	v_mfma_f32_32x32x16_bf16 v[82:97], v[236:239], v[110:113], v[82:97]
	ds_read_b128 v[236:239], v202 offset:49280
	s_waitcnt lgkmcnt(4)
	v_mfma_f32_32x32x16_bf16 v[66:81], v[240:243], v[106:109], v[66:81]
	ds_read_b64_tr_b16 v[212:213], v1 offset:0x0
	ds_read_b64_tr_b16 v[214:215], v1 offset:0x800
	ds_read_b64_tr_b16 v[216:217], v1 offset:0x200
	ds_read_b64_tr_b16 v[218:219], v1 offset:0xa00
	ds_read_b64_tr_b16 v[220:221], v1 offset:0x400
	ds_read_b64_tr_b16 v[222:223], v1 offset:0xc00
	ds_read_b64_tr_b16 v[224:225], v1 offset:0x600
	ds_read_b64_tr_b16 v[226:227], v1 offset:0xe00
	ds_read_b128 v[240:243], v202 offset:57472
	s_waitcnt lgkmcnt(12)
	v_mfma_f32_32x32x16_bf16 v[82:97], v[244:247], v[106:109], v[82:97]
	s_waitcnt lgkmcnt(11)
	v_mfma_f32_32x32x16_bf16 v[66:81], v[172:175], v[102:105], v[66:81]
	s_waitcnt lgkmcnt(10)
	v_mfma_f32_32x32x16_bf16 v[82:97], v[232:235], v[102:105], v[82:97]
	s_waitcnt lgkmcnt(9)
	v_mfma_f32_32x32x16_bf16 v[66:81], v[236:239], v[98:101], v[66:81]
	s_waitcnt lgkmcnt(0)
	v_mfma_f32_32x32x16_bf16 v[82:97], v[240:243], v[98:101], v[82:97]
	ds_read_b64_tr_b16 v[248:249], v1 offset:0x1000
	ds_read_b64_tr_b16 v[250:251], v1 offset:0x1800
	ds_read_b64_tr_b16 v[172:173], v1 offset:0x1200
	ds_read_b64_tr_b16 v[174:175], v1 offset:0x1a00
	ds_read_b64_tr_b16 v[232:233], v1 offset:0x1400
	ds_read_b64_tr_b16 v[234:235], v1 offset:0x1c00
	s_waitcnt lgkmcnt(13)
	v_mfma_f32_32x32x16_bf16 v[2:17], v[148:151], v[212:215], v[2:17]
	ds_read_b64_tr_b16 v[236:237], v1 offset:0x1600
	ds_read_b64_tr_b16 v[238:239], v1 offset:0x1e00
	s_waitcnt lgkmcnt(13)
; __device__ __forceinline__ void sel_mask_tile(f32x16& p0, f32x16& p1, unsigned wlo, unsigned whi, int hi) {
;     const unsigned NEGB = 0xff800000u;
;     const unsigned lo = wlo >> (4 * hi), h2 = whi >> (4 * hi);
; #pragma unroll
;     for (int r = 0; r < 16; ++r) {
;         const int c = (r & 3) + 8 * (r >> 2);
;         const unsigned m0 = (unsigned)__builtin_amdgcn_sbfe((int)lo, c, 1), m1 = (unsigned)__builtin_amdgcn_sbfe((int)h2, c, 1);
;         p0[r] = __uint_as_float((__float_as_uint(p0[r]) & m0) | (NEGB & ~m0));
;         p1[r] = __uint_as_float((__float_as_uint(p1[r]) & m1) | (NEGB & ~m1));
;     }
; }
; __device__ __forceinline__ void partialSM(f32x16& p0, f32x16& p1, float& m_reg, float& mn, float& alpha) {
;     float pmax = p0[0];
; #pragma unroll
;     for (int r = 1; r < 16; ++r) pmax = fmaxf(pmax, p0[r]);
; #pragma unroll
;     for (int r = 0; r < 16; ++r) pmax = fmaxf(pmax, p1[r]);
;     { auto rr = __builtin_amdgcn_permlane32_swap(__float_as_uint(pmax), __float_as_uint(pmax), false, false);
;       pmax = fmaxf(__uint_as_float(rr[0]), __uint_as_float(rr[1])); }
;     constexpr float C2 = 1.4426950408889634f * SCALE;
;     if (__builtin_expect(__all((pmax - m_reg) * SCALE <= THR), 1)) { mn = m_reg; alpha = 1.f; }
;     else { mn = fmaxf(m_reg, pmax); alpha = __builtin_amdgcn_exp2f((m_reg - mn) * C2); m_reg = mn; }
; template <int VB>
; __device__ __forceinline__ void pv_tile(f32x16* o, int vb0, bf16x8 pa0, bf16x8 pa1, bf16x8 pa2, bf16x8 pa3) {
;     ...
;     PV_D0(0); PV_D0(1); PV_D0(2); PV_D0(3);
	v_mfma_f32_32x32x16_bf16 v[50:65], v[148:151], v[216:219], v[50:65]
	ds_read_b64_tr_b16 v[240:241], v1 offset:0x2000
	ds_read_b64_tr_b16 v[242:243], v1 offset:0x2800
	s_waitcnt lgkmcnt(13)
	v_mfma_f32_32x32x16_bf16 v[34:49], v[148:151], v[220:223], v[34:49]
	ds_read_b64_tr_b16 v[244:245], v1 offset:0x2200
	ds_read_b64_tr_b16 v[246:247], v1 offset:0x2a00
	s_waitcnt lgkmcnt(13)
	v_mfma_f32_32x32x16_bf16 v[18:33], v[148:151], v[224:227], v[18:33]
	ds_read_b64_tr_b16 v[224:225], v1 offset:0x2400
	ds_read_b64_tr_b16 v[226:227], v1 offset:0x2c00
	s_waitcnt lgkmcnt(12)
	v_mfma_f32_32x32x16_bf16 v[2:17], v[152:155], v[248:251], v[2:17]
	ds_read_b64_tr_b16 v[248:249], v1 offset:0x2600
	ds_read_b64_tr_b16 v[250:251], v1 offset:0x2e00
	s_waitcnt lgkmcnt(12)
	v_mfma_f32_32x32x16_bf16 v[50:65], v[152:155], v[172:175], v[50:65]
	ds_read_b64_tr_b16 v[172:173], v1 offset:0x3000
	ds_read_b64_tr_b16 v[174:175], v1 offset:0x3800
	s_waitcnt lgkmcnt(12)
	v_mfma_f32_32x32x16_bf16 v[34:49], v[152:155], v[232:235], v[34:49]
	ds_read_b64_tr_b16 v[232:233], v1 offset:0x3200
	ds_read_b64_tr_b16 v[234:235], v1 offset:0x3a00
	s_waitcnt lgkmcnt(12)
	v_mfma_f32_32x32x16_bf16 v[18:33], v[152:155], v[236:239], v[18:33]
	ds_read_b64_tr_b16 v[236:237], v1 offset:0x3400
	ds_read_b64_tr_b16 v[238:239], v1 offset:0x3c00
	s_waitcnt lgkmcnt(12)
	v_mfma_f32_32x32x16_bf16 v[2:17], v[156:159], v[240:243], v[2:17]
	ds_read_b64_tr_b16 v[240:241], v1 offset:0x3600
	ds_read_b64_tr_b16 v[242:243], v1 offset:0x3e00
	s_waitcnt lgkmcnt(12)
	v_mfma_f32_32x32x16_bf16 v[50:65], v[156:159], v[244:247], v[50:65]
	s_waitcnt lgkmcnt(10)
	v_mfma_f32_32x32x16_bf16 v[34:49], v[156:159], v[224:227], v[34:49]
	s_waitcnt lgkmcnt(8)
	v_mfma_f32_32x32x16_bf16 v[18:33], v[156:159], v[248:251], v[18:33]
	s_waitcnt lgkmcnt(6)
	v_mfma_f32_32x32x16_bf16 v[2:17], v[208:211], v[172:175], v[2:17]
	s_waitcnt lgkmcnt(4)
	v_mfma_f32_32x32x16_bf16 v[50:65], v[208:211], v[232:235], v[50:65]
	s_waitcnt lgkmcnt(2)
	v_mfma_f32_32x32x16_bf16 v[34:49], v[208:211], v[236:239], v[34:49]
	s_waitcnt lgkmcnt(0)
	v_mfma_f32_32x32x16_bf16 v[18:33], v[208:211], v[240:243], v[18:33]
	s_waitcnt vmcnt(0)
	ds_write_b128 v204, v[138:141] offset:32768
	ds_write_b128 v204, v[142:145] offset:40960
	s_waitcnt lgkmcnt(0)
	s_barrier
	s_nop 0
	s_waitcnt vmcnt(4)
	v_lshrrev_b32_e32 v160, v163, v146
	v_lshrrev_b32_e32 v161, v163, v147
	v_bfe_i32 v146, v160, 0, 1
	v_bfe_i32 v147, v161, 0, 1
	v_bitop3_b32 v146, v66, s74, v146 bitop3:0xe4
	v_bitop3_b32 v66, v82, s74, v147 bitop3:0xe4
	v_bfe_i32 v82, v160, 1, 1
	v_bfe_i32 v147, v161, 1, 1
	v_bitop3_b32 v82, v67, s74, v82 bitop3:0xe4
	v_bitop3_b32 v67, v83, s74, v147 bitop3:0xe4
	v_bfe_i32 v83, v160, 2, 1
	v_bfe_i32 v147, v161, 2, 1
	v_bitop3_b32 v83, v68, s74, v83 bitop3:0xe4
	v_bitop3_b32 v68, v84, s74, v147 bitop3:0xe4
	v_bfe_i32 v84, v160, 3, 1
	v_bfe_i32 v148, v161, 3, 1
	v_bitop3_b32 v147, v69, s74, v84 bitop3:0xe4
	v_bfe_i32 v84, v160, 8, 1
	v_bitop3_b32 v69, v85, s74, v148 bitop3:0xe4
	v_bfe_i32 v85, v161, 8, 1
	v_bitop3_b32 v148, v70, s74, v84 bitop3:0xe4
	v_bfe_i32 v84, v160, 9, 1
	v_bitop3_b32 v70, v86, s74, v85 bitop3:0xe4
	v_bfe_i32 v85, v161, 9, 1
	v_bitop3_b32 v149, v71, s74, v84 bitop3:0xe4
	v_bfe_i32 v84, v160, 10, 1
	v_bitop3_b32 v71, v87, s74, v85 bitop3:0xe4
	v_bfe_i32 v85, v161, 10, 1
	v_bitop3_b32 v87, v72, s74, v84 bitop3:0xe4
	v_bfe_i32 v84, v160, 11, 1
	v_bitop3_b32 v72, v88, s74, v85 bitop3:0xe4
	v_bfe_i32 v85, v161, 11, 1
	v_bitop3_b32 v88, v73, s74, v84 bitop3:0xe4
	v_bfe_i32 v73, v160, 16, 1
	v_bitop3_b32 v84, v89, s74, v85 bitop3:0xe4
	v_bfe_i32 v85, v161, 16, 1
	v_bitop3_b32 v89, v74, s74, v73 bitop3:0xe4
	v_bfe_i32 v73, v160, 17, 1
	v_bfe_i32 v74, v161, 17, 1
	v_bitop3_b32 v85, v90, s74, v85 bitop3:0xe4
	v_bitop3_b32 v90, v75, s74, v73 bitop3:0xe4
	v_bitop3_b32 v86, v91, s74, v74 bitop3:0xe4
	v_bfe_i32 v73, v160, 18, 1
	v_bfe_i32 v74, v161, 18, 1
	v_bitop3_b32 v91, v76, s74, v73 bitop3:0xe4
	v_bitop3_b32 v76, v92, s74, v74 bitop3:0xe4
	v_bfe_i32 v73, v160, 19, 1
	v_bfe_i32 v74, v161, 19, 1
	v_bitop3_b32 v92, v77, s74, v73 bitop3:0xe4
	v_bitop3_b32 v77, v93, s74, v74 bitop3:0xe4
	v_bfe_i32 v73, v160, 24, 1
	v_bfe_i32 v74, v161, 24, 1
	v_bitop3_b32 v93, v78, s74, v73 bitop3:0xe4
	v_bitop3_b32 v78, v94, s74, v74 bitop3:0xe4
	v_bfe_i32 v73, v160, 25, 1
	v_bfe_i32 v74, v161, 25, 1
	v_bitop3_b32 v79, v79, s74, v73 bitop3:0xe4
	v_bitop3_b32 v73, v95, s74, v74 bitop3:0xe4
	v_bfe_i32 v74, v160, 26, 1
	v_bfe_i32 v75, v161, 26, 1
	v_bitop3_b32 v80, v80, s74, v74 bitop3:0xe4
	v_bitop3_b32 v74, v96, s74, v75 bitop3:0xe4
	v_bfe_i32 v75, v160, 27, 1
	v_bfe_i32 v94, v161, 27, 1
	v_bitop3_b32 v81, v81, s74, v75 bitop3:0xe4
	v_bitop3_b32 v75, v97, s74, v94 bitop3:0xe4
	v_max_f32_e32 v94, v146, v82
	v_max3_f32 v94, v94, v83, v147
	v_max3_f32 v94, v94, v148, v149
	v_max3_f32 v94, v94, v87, v88
	v_max3_f32 v94, v94, v89, v90
	v_max3_f32 v94, v94, v91, v92
	v_max3_f32 v94, v94, v93, v79
	v_max3_f32 v94, v94, v80, v81
	v_max3_f32 v94, v94, v66, v67
	v_max3_f32 v94, v94, v68, v69
	v_max3_f32 v94, v94, v70, v71
	v_max3_f32 v94, v94, v72, v84
	v_max3_f32 v94, v94, v85, v86
	v_max3_f32 v94, v94, v76, v77
	v_max3_f32 v94, v94, v78, v73
	v_max3_f32 v94, v94, v74, v75
	v_mov_b32_e32 v95, v94
	s_nop 1
	v_permlane32_swap_b32_e32 v94, v95
	v_max_f32_e32 v94, v94, v95
	v_sub_f32_e32 v95, v94, v206
	v_mul_f32_e32 v95, 0x3db504f3, v95
	v_cmp_ge_f32_e32 vcc, s75, v95
	s_cmp_eq_u64 vcc, exec
	s_cselect_b64 s[6:7], -1, 0
	s_cbranch_scc1 .Lp5_b1fast
	v_max_f32_e32 v94, v206, v94
	v_sub_f32_e32 v96, v206, v94
	v_mul_f32_e32 v96, 0x3e0293ee, v96
	v_exp_f32_e32 v96, v96

; __device__ __forceinline__ void partialSM(f32x16& p0, f32x16& p1, float& m_reg, float& mn, float& alpha) {
;     ...
;     else { mn = fmaxf(m_reg, pmax); alpha = __builtin_amdgcn_exp2f((m_reg - mn) * C2); m_reg = mn; }
;     const float mnL = -mn * C2;
; #pragma unroll
;     for (int r = 0; r < 16; ++r) p0[r] = fmaf(p0[r], C2, mnL);
; #pragma unroll
;     for (int r = 0; r < 16; ++r) p1[r] = fmaf(p1[r], C2, mnL);
; #pragma unroll
;     for (int r = 0; r < 16; ++r) p0[r] = __builtin_amdgcn_exp2f(p0[r]);
; }
; __device__ __forceinline__ void finishSM(f32x16& p0, f32x16& p1, float alpha, float& l_reg, bf16x8& pa0, bf16x8& pa1, bf16x8& pa2, bf16x8& pa3) {
; #pragma unroll
;     for (int r = 0; r < 16; ++r) p1[r] = __builtin_amdgcn_exp2f(p1[r]);
;     float ps = 0;
; #pragma unroll
;     for (int r = 0; r < 16; ++r) ps += p0[r];
; #pragma unroll
;     for (int r = 0; r < 16; ++r) ps += p1[r];
;     { auto rr = __builtin_amdgcn_permlane32_swap(__float_as_uint(ps), __float_as_uint(ps), false, false);
;       ps = __uint_as_float(rr[0]) + __uint_as_float(rr[1]); }
;     l_reg = l_reg * alpha + ps;
;     ...
;     PK4(p0, 0, pa0); PK4(p0, 8, pa1); PK4(p1, 0, pa2); PK4(p1, 8, pa3);
.LBB0_1303:
	v_cndmask_b32_e64 v206, v94, v206, s[6:7]
	v_mul_f32_e32 v207, 0xbe0293ee, v206
	v_fmamk_f32 v94, v146, 0x3e0293ee, v207
	v_fmamk_f32 v82, v82, 0x3e0293ee, v207
	v_fmamk_f32 v83, v83, 0x3e0293ee, v207
	v_fmamk_f32 v95, v147, 0x3e0293ee, v207
	v_fmamk_f32 v96, v148, 0x3e0293ee, v207
	v_fmamk_f32 v97, v149, 0x3e0293ee, v207
	v_fmamk_f32 v87, v87, 0x3e0293ee, v207
	v_fmamk_f32 v88, v88, 0x3e0293ee, v207
	v_fmamk_f32 v89, v89, 0x3e0293ee, v207
	v_fmamk_f32 v90, v90, 0x3e0293ee, v207
	v_fmamk_f32 v91, v91, 0x3e0293ee, v207
	v_fmamk_f32 v92, v92, 0x3e0293ee, v207
	v_fmamk_f32 v93, v93, 0x3e0293ee, v207
	v_fmamk_f32 v79, v79, 0x3e0293ee, v207
	v_fmamk_f32 v80, v80, 0x3e0293ee, v207
	v_fmamk_f32 v81, v81, 0x3e0293ee, v207
	v_exp_f32_e32 v146, v94
	v_exp_f32_e32 v147, v82
	v_exp_f32_e32 v148, v83
	v_exp_f32_e32 v159, v95
	v_exp_f32_e32 v160, v96
	v_exp_f32_e32 v161, v97
	v_exp_f32_e32 v149, v87
	v_exp_f32_e32 v158, v88
	v_exp_f32_e32 v150, v89
	v_exp_f32_e32 v151, v90
	v_exp_f32_e32 v155, v91
	v_exp_f32_e32 v157, v92
	v_exp_f32_e32 v152, v93
	v_exp_f32_e32 v153, v79
	v_exp_f32_e32 v154, v80
	v_exp_f32_e32 v156, v81
	v_fmamk_f32 v210, v71, 0x3e0293ee, v207
	v_fmamk_f32 v209, v78, 0x3e0293ee, v207
	v_fmamk_f32 v217, v66, 0x3e0293ee, v207
	v_fmamk_f32 v218, v67, 0x3e0293ee, v207
	v_fmamk_f32 v219, v68, 0x3e0293ee, v207
	v_fmamk_f32 v220, v69, 0x3e0293ee, v207
	v_fmamk_f32 v221, v70, 0x3e0293ee, v207
	v_fmamk_f32 v211, v72, 0x3e0293ee, v207
	v_fmamk_f32 v212, v84, 0x3e0293ee, v207
	v_fmamk_f32 v213, v85, 0x3e0293ee, v207
	v_fmamk_f32 v214, v86, 0x3e0293ee, v207
	v_fmamk_f32 v215, v76, 0x3e0293ee, v207
	v_fmamk_f32 v216, v77, 0x3e0293ee, v207
	v_fmamk_f32 v222, v73, 0x3e0293ee, v207
	v_fmamk_f32 v223, v74, 0x3e0293ee, v207
	v_fmac_f32_e32 v207, 0x3e0293ee, v75
	v_exp_f32_e32 v211, v211
	v_exp_f32_e32 v212, v212
	v_exp_f32_e32 v213, v213
	v_exp_f32_e32 v214, v214
	v_exp_f32_e32 v215, v215
	v_exp_f32_e32 v216, v216
	v_exp_f32_e32 v207, v207
	v_exp_f32_e32 v250, v219
	v_exp_f32_e32 v219, v209
	v_add_f32_e32 v209, v147, v146
	v_add_f32_e32 v209, v148, v209
	v_add_f32_e32 v209, v159, v209
	v_add_f32_e32 v209, v160, v209
	v_add_f32_e32 v209, v161, v209
	v_add_f32_e32 v209, v149, v209
	v_add_f32_e32 v209, v158, v209
	v_add_f32_e32 v209, v150, v209
	v_add_f32_e32 v209, v151, v209
	v_add_f32_e32 v209, v155, v209
	v_add_f32_e32 v209, v157, v209
	v_exp_f32_e32 v248, v217
	v_add_f32_e32 v209, v152, v209
	v_exp_f32_e32 v249, v218
	v_add_f32_e32 v209, v153, v209
	v_add_f32_e32 v209, v154, v209
	v_exp_f32_e32 v251, v220
	v_add_f32_e32 v209, v156, v209
	v_exp_f32_e32 v217, v221
	v_add_f32_e32 v209, v248, v209
	v_exp_f32_e32 v218, v210
	v_add_f32_e32 v209, v249, v209
	v_add_f32_e32 v209, v250, v209
	v_add_f32_e32 v209, v251, v209
	v_add_f32_e32 v209, v217, v209
	v_add_f32_e32 v209, v218, v209
	v_add_f32_e32 v209, v211, v209
	v_add_f32_e32 v209, v212, v209
	v_add_f32_e32 v209, v213, v209
	v_exp_f32_e32 v220, v222
	v_add_f32_e32 v209, v214, v209
	v_exp_f32_e32 v221, v223
	v_add_f32_e32 v209, v215, v209
	v_add_f32_e32 v209, v216, v209
	v_add_f32_e32 v209, v219, v209
	v_add_f32_e32 v209, v220, v209
	v_add_f32_e32 v209, v221, v209
	v_add_f32_e32 v209, v207, v209
	v_cvt_pk_bf16_f32 v146, v146, v147
	v_cvt_pk_bf16_f32 v147, v148, v159
	v_cvt_pk_bf16_f32 v148, v160, v161
	v_cvt_pk_bf16_f32 v149, v149, v158
	v_cvt_pk_bf16_f32 v150, v150, v151
	v_cvt_pk_bf16_f32 v151, v155, v157
	v_cvt_pk_bf16_f32 v152, v152, v153
	v_cvt_pk_bf16_f32 v153, v154, v156
	v_cvt_pk_bf16_f32 v154, v248, v249
	v_cvt_pk_bf16_f32 v155, v250, v251
	v_cvt_pk_bf16_f32 v156, v217, v218
	v_cvt_pk_bf16_f32 v157, v211, v212
	v_cvt_pk_bf16_f32 v158, v213, v214
	v_cvt_pk_bf16_f32 v159, v215, v216
	v_cvt_pk_bf16_f32 v160, v219, v220
	v_cvt_pk_bf16_f32 v161, v221, v207
	s_waitcnt lgkmcnt(0)
	s_barrier
	ds_read_b128 v[66:69], v199 offset:32768
	ds_read_b128 v[70:73], v199 offset:40960
	ds_read_b128 v[172:175], v200 offset:32768
	ds_read_b128 v[224:227], v200 offset:40960
	ds_read_b128 v[232:235], v201 offset:32768
	ds_read_b128 v[236:239], v201 offset:40960
	ds_read_b128 v[240:243], v202 offset:32768
	ds_read_b128 v[244:247], v202 offset:40960
	s_waitcnt vmcnt(0)
	ds_write_b128 v197, v[130:133]
	ds_write_b128 v198, v[134:137]
	global_load_dwordx2 v[228:229], v179, s[68:69]
	s_add_i32 s98, s82, 2
	s_cmp_gt_u32 s98, s81
	s_cbranch_scc1 .Lp5_a2
	s_add_u32 s98, s16, 0x60000
	s_addc_u32 s99, s17, 0
	global_load_dwordx4 v[130:133], v188, s[98:99]
	s_add_u32 s98, s16, 0x70000
	s_addc_u32 s99, s17, 0
	global_load_dwordx4 v[134:137], v188, s[98:99]
	s_add_u32 s98, s100, 0x60000
	s_addc_u32 s99, s101, 0
	global_load_dwordx4 v[138:141], v188, s[98:99]
	s_add_u32 s98, s100, 0x70000
	s_addc_u32 s99, s101, 0
	global_load_dwordx4 v[142:145], v188, s[98:99]
; template <int KB>
; __device__ __forceinline__ void qkt(f32x16& p0, f32x16& p1, const char* K_lds, int r32, int hi, const bf16x8* qr) {
;     p0 = f32x16{}; p1 = f32x16{};
;     const char* kb[4];
; #pragma unroll
;     for (int dd = 0; dd < 4; ++dd) kb[dd] = K_lds + KB * SHM_K + KSWZ(r32, (dd * 16 + hi * 8) * 2);
; #pragma unroll
;     for (int d0 = 0; d0 < 8; ++d0) { const char* a = kb[d0 & 3] + (d0 >> 2) * 128;
;         bf16x8 b0 = *reinterpret_cast<const bf16x8*>(a);
;         bf16x8 b1 = *reinterpret_cast<const bf16x8*>(a + 32 * 256);
;         p0 = __builtin_amdgcn_mfma_f32_32x32x16_bf16(b0, qr[d0], p0, 0, 0, 0);
;         p1 = __builtin_amdgcn_mfma_f32_32x32x16_bf16(b1, qr[d0], p1, 0, 0, 0); }
; }
.Lp5_a2:
	s_waitcnt lgkmcnt(7)
	v_mfma_f32_32x32x16_bf16 v[82:97], v[66:69], v[126:129], 0
	s_waitcnt lgkmcnt(6)
	v_mfma_f32_32x32x16_bf16 v[66:81], v[70:73], v[126:129], 0
	s_waitcnt lgkmcnt(5)
	v_mfma_f32_32x32x16_bf16 v[82:97], v[172:175], v[122:125], v[82:97]
	ds_read_b128 v[172:175], v199 offset:32896
	s_waitcnt lgkmcnt(5)
	v_mfma_f32_32x32x16_bf16 v[66:81], v[224:227], v[122:125], v[66:81]
	ds_read_b128 v[224:227], v199 offset:41088
	s_waitcnt lgkmcnt(5)
	v_mfma_f32_32x32x16_bf16 v[82:97], v[232:235], v[118:121], v[82:97]
	ds_read_b128 v[232:235], v200 offset:32896
	s_waitcnt lgkmcnt(5)
	v_mfma_f32_32x32x16_bf16 v[66:81], v[236:239], v[118:121], v[66:81]
	ds_read_b128 v[236:239], v200 offset:41088
	s_waitcnt lgkmcnt(5)
	v_mfma_f32_32x32x16_bf16 v[82:97], v[240:243], v[114:117], v[82:97]
	ds_read_b128 v[240:243], v201 offset:32896
	s_waitcnt lgkmcnt(5)
	v_mfma_f32_32x32x16_bf16 v[66:81], v[244:247], v[114:117], v[66:81]
	ds_read_b128 v[244:247], v201 offset:41088
	s_waitcnt lgkmcnt(5)
	v_mfma_f32_32x32x16_bf16 v[82:97], v[172:175], v[110:113], v[82:97]
	ds_read_b128 v[172:175], v202 offset:32896
	s_waitcnt lgkmcnt(5)
	v_mfma_f32_32x32x16_bf16 v[66:81], v[224:227], v[110:113], v[66:81]
	ds_read_b128 v[224:227], v202 offset:41088
	s_waitcnt lgkmcnt(5)
	v_mfma_f32_32x32x16_bf16 v[82:97], v[232:235], v[106:109], v[82:97]
	ds_read_b64_tr_b16 v[212:213], v1 offset:0x4000
	ds_read_b64_tr_b16 v[214:215], v1 offset:0x4800
	ds_read_b64_tr_b16 v[216:217], v1 offset:0x4200
	ds_read_b64_tr_b16 v[218:219], v1 offset:0x4a00
	ds_read_b64_tr_b16 v[220:221], v1 offset:0x4400
	ds_read_b64_tr_b16 v[222:223], v1 offset:0x4c00
	ds_read_b64_tr_b16 v[248:249], v1 offset:0x4600
	ds_read_b64_tr_b16 v[250:251], v1 offset:0x4e00
	s_waitcnt lgkmcnt(12)
	v_mfma_f32_32x32x16_bf16 v[66:81], v[236:239], v[106:109], v[66:81]
	s_waitcnt lgkmcnt(11)
	v_mfma_f32_32x32x16_bf16 v[82:97], v[240:243], v[102:105], v[82:97]
	s_waitcnt lgkmcnt(10)
	v_mfma_f32_32x32x16_bf16 v[66:81], v[244:247], v[102:105], v[66:81]
	s_waitcnt lgkmcnt(9)
	v_mfma_f32_32x32x16_bf16 v[82:97], v[172:175], v[98:101], v[82:97]
	s_waitcnt lgkmcnt(8)
	v_mfma_f32_32x32x16_bf16 v[66:81], v[224:227], v[98:101], v[66:81]
	s_add_i32 s82, s82, 2
	s_cmp_le_u32 s82, s81
	s_cselect_b64 s[36:37], -1, 0
	s_cselect_b32 s76, 1, 0
	s_cmp_gt_u32 s82, s81
	s_cbranch_scc1 .Lp5_skip_ld
